# ssd-readlane-broadcast
# speedup vs baseline: 1.0046x; 1.0046x over previous
; __device__ __forceinline__ void ssd_item(const Params& p, LAS unsigned char* lds, int b, int head, bool sample) {
;     ...
;         const float dtl = P.dt;
;         float cs = dtl * a_h;
; #pragma unroll
;         for (int o = 1; o < 64; o <<= 1) { const float t = __shfl_up(cs, o); if (lane >= o) cs += t; }
;         const float cs_last = __shfl(cs, 63);
;         const float wl = dtl * __expf(cs_last - cs);
;         if (wave == 0) { acs[lane] = cs; dtv[lane] = dtl; }
.LBB0_1249:
	s_waitcnt vmcnt(0)
	v_mul_f32_e64 v2, v1, -v77
	s_andn2_b64 vcc, exec, s[86:87]
	s_nop 1
	v_add_f32_dpp v2, v2, v2 row_shr:1 row_mask:0xf bank_mask:0xf bound_ctrl:0
	s_nop 1
	v_add_f32_dpp v2, v2, v2 row_shr:2 row_mask:0xf bank_mask:0xf bound_ctrl:0
	s_nop 1
	v_add_f32_dpp v2, v2, v2 row_shr:4 row_mask:0xf bank_mask:0xf bound_ctrl:0
	s_nop 1
	v_add_f32_dpp v2, v2, v2 row_shr:8 row_mask:0xf bank_mask:0xf bound_ctrl:0
	s_nop 1
	v_add_f32_dpp v2, v2, v2 row_bcast:15 row_mask:0xa bank_mask:0xf
	s_nop 1
	v_add_f32_dpp v2, v2, v2 row_bcast:31 row_mask:0xc bank_mask:0xf
	s_nop 0
	v_readlane_b32 s98, v2, 63
	s_nop 1
	v_mov_b32_e32 v166, s98
	s_cbranch_vccnz .LBB0_1251
	ds_write_b32 v108, v2
	ds_write_b32 v107, v1
